# row pass (post-mixer): next rows' y lines requested together with the x loads so the compiler's immediately-waited y loads hit the cache
# baseline (speedup 1.0000x reference)
.LBB0_201:
	v_lshlrev_b64 v[2:3], 11, v[2:3]
	v_lshl_add_u64 v[2:3], v[134:135], 0, v[2:3]
	v_mov_b32_e32 v163, v1
	v_lshl_add_u64 v[2:3], v[2:3], 0, v[162:163]
	v_lshlrev_b64 v[98:99], 11, v[132:133]
	v_lshl_add_u64 v[98:99], v[164:165], 0, v[98:99]
	global_load_dwordx2 v[106:107], v[98:99], off
	global_load_dwordx2 v[106:107], v[98:99], off offset:512
	global_load_dwordx2 v[106:107], v[98:99], off offset:1024
	global_load_dwordx2 v[106:107], v[98:99], off offset:1536
	global_load_dwordx2 v[98:99], v[2:3], off
	global_load_dwordx2 v[106:107], v[2:3], off offset:512
	global_load_dwordx2 v[110:111], v[2:3], off offset:1024
	s_nop 0
	global_load_dwordx2 v[2:3], v[2:3], off offset:1536
	s_waitcnt vmcnt(3)
	v_lshlrev_b32_e32 v96, 16, v98
	v_and_b32_e32 v97, 0xffff0000, v98
	v_lshlrev_b32_e32 v98, 16, v99
	v_and_b32_e32 v99, 0xffff0000, v99
	s_waitcnt vmcnt(2)
	v_lshlrev_b32_e32 v104, 16, v106
	v_and_b32_e32 v105, 0xffff0000, v106
	v_lshlrev_b32_e32 v106, 16, v107
	v_and_b32_e32 v107, 0xffff0000, v107
	s_waitcnt vmcnt(1)
	v_lshlrev_b32_e32 v108, 16, v110
	v_and_b32_e32 v109, 0xffff0000, v110
	v_lshlrev_b32_e32 v110, 16, v111
	v_and_b32_e32 v111, 0xffff0000, v111
	s_waitcnt vmcnt(0)
	v_lshlrev_b32_e32 v112, 16, v2
	v_and_b32_e32 v113, 0xffff0000, v2
	v_lshlrev_b32_e32 v114, 16, v3
	v_and_b32_e32 v115, 0xffff0000, v3

.LBB0_211:
	s_waitcnt vmcnt(3)
	v_lshlrev_b64 v[132:133], 11, v[214:215]
	v_lshl_add_u64 v[132:133], v[216:217], 0, v[132:133]
	v_mov_b32_e32 v163, v1
	v_lshl_add_u64 v[132:133], v[132:133], 0, v[162:163]
	v_lshlrev_b64 v[134:135], 11, v[230:231]
	v_lshl_add_u64 v[134:135], v[164:165], 0, v[134:135]
	global_load_dwordx2 v[138:139], v[134:135], off
	global_load_dwordx2 v[138:139], v[134:135], off offset:512
	global_load_dwordx2 v[138:139], v[134:135], off offset:1024
	global_load_dwordx2 v[138:139], v[134:135], off offset:1536
	global_load_dwordx2 v[134:135], v[132:133], off
	global_load_dwordx2 v[138:139], v[132:133], off offset:512
	global_load_dwordx2 v[142:143], v[132:133], off offset:1024
	global_load_dwordx2 v[146:147], v[132:133], off offset:1536
	s_waitcnt vmcnt(3)
	v_lshlrev_b32_e32 v132, 16, v134
	v_and_b32_e32 v133, 0xffff0000, v134
	v_lshlrev_b32_e32 v134, 16, v135
	v_and_b32_e32 v135, 0xffff0000, v135
	s_waitcnt vmcnt(2)
	v_lshlrev_b32_e32 v136, 16, v138
	v_and_b32_e32 v137, 0xffff0000, v138
	v_lshlrev_b32_e32 v138, 16, v139
	v_and_b32_e32 v139, 0xffff0000, v139
	s_waitcnt vmcnt(1)
	v_lshlrev_b32_e32 v140, 16, v142
	v_and_b32_e32 v141, 0xffff0000, v142
	v_lshlrev_b32_e32 v142, 16, v143
	v_and_b32_e32 v143, 0xffff0000, v143
	s_waitcnt vmcnt(0)
	v_lshlrev_b32_e32 v144, 16, v146
	v_and_b32_e32 v145, 0xffff0000, v146
	v_lshlrev_b32_e32 v146, 16, v147
	v_and_b32_e32 v147, 0xffff0000, v147
